# hand-written PEER expert main loop: batched 4-expert reduction+gelu, sorted expert list, rcp instead of IEEE div
# speedup vs baseline: 1.0574x; 1.0574x over previous
.LBB0_1944:
	s_waitcnt vmcnt(0) lgkmcnt(0)
	v_readfirstlane_b32 s100, v206
	s_lshr_b32 s100, s100, 6
	s_lshl_b32 s100, s100, 12
	s_add_u32 s100, s100, 0x4000
	v_and_b32_e32 v255, 63, v206
	v_lshl_add_u32 v255, v255, 2, s100
	ds_write_b32 v255, v0 offset:256
	ds_write_b32 v255, v1 offset:512
	ds_write_b32 v255, v2 offset:768
	ds_write_b32 v255, v3 offset:1024
	ds_write_b32 v255, v4 offset:1280
	ds_write_b32 v255, v5 offset:1536
	ds_write_b32 v255, v6 offset:1792
	ds_write_b32 v255, v7 offset:2048
	ds_write_b32 v255, v8 offset:2304
	ds_write_b32 v255, v9 offset:2560
	ds_write_b32 v255, v10 offset:2816
	ds_write_b32 v255, v11 offset:3072
	v_mov_b32_e32 v0, 0
	ds_write_b32 v255, v0
	ds_read_b64 v[2:3], v175
	ds_read_b64 v[4:5], v175 offset:1024
	s_waitcnt lgkmcnt(0)
	v_lshrrev_b32_e32 v6, 8, v2
	v_lshrrev_b32_e32 v7, 8, v4
	v_lshl_add_u32 v6, v6, 2, s100
	v_lshl_add_u32 v7, v7, 2, s100
	v_mov_b32_e32 v0, 1
	ds_add_rtn_u32 v8, v6, v0
	ds_add_rtn_u32 v9, v7, v0
	s_waitcnt lgkmcnt(0)
	ds_read_b32 v10, v255
	s_waitcnt lgkmcnt(0)
	v_mov_b32_e32 v11, v10
	s_nop 1
	v_add_u32_dpp v11, v11, v11 row_shr:1 row_mask:0xf bank_mask:0xf bound_ctrl:1
	s_nop 1
	v_add_u32_dpp v11, v11, v11 row_shr:2 row_mask:0xf bank_mask:0xf bound_ctrl:1
	s_nop 1
	v_add_u32_dpp v11, v11, v11 row_shr:4 row_mask:0xf bank_mask:0xf bound_ctrl:1
	s_nop 1
	v_add_u32_dpp v11, v11, v11 row_shr:8 row_mask:0xf bank_mask:0xf bound_ctrl:1
	s_nop 1
	v_add_u32_dpp v11, v11, v11 row_bcast:15 row_mask:0xa bank_mask:0xf
	s_nop 1
	v_add_u32_dpp v11, v11, v11 row_bcast:31 row_mask:0xc bank_mask:0xf
	s_nop 1
	v_sub_u32_e32 v11, v11, v10
	ds_write_b32 v255, v11
	s_waitcnt lgkmcnt(0)
	ds_read_b32 v10, v6
	ds_read_b32 v11, v7
	s_waitcnt lgkmcnt(0)
	v_add_u32_e32 v8, v8, v10
	v_add_u32_e32 v9, v9, v11
	v_lshl_add_u32 v8, v8, 4, v174
	v_lshl_add_u32 v9, v9, 4, v174
	ds_write_b64 v8, v[2:3]
	ds_write_b64 v9, v[4:5]
	ds_read_b32 v0, v255 offset:256
	ds_read_b32 v1, v255 offset:512
	ds_read_b32 v2, v255 offset:768
	ds_read_b32 v3, v255 offset:1024
	ds_read_b32 v4, v255 offset:1280
	ds_read_b32 v5, v255 offset:1536
	ds_read_b32 v6, v255 offset:1792
	ds_read_b32 v7, v255 offset:2048
	ds_read_b32 v8, v255 offset:2304
	ds_read_b32 v9, v255 offset:2560
	ds_read_b32 v10, v255 offset:2816
	ds_read_b32 v11, v255 offset:3072
	s_waitcnt lgkmcnt(0)
	v_pk_add_f32 v[34:35], v[34:35], 1.0 op_sel_hi:[1,0]
	v_pk_add_f32 v[20:21], v[20:21], 1.0 op_sel_hi:[1,0]
	v_pk_fma_f32 v[132:133], v[0:1], v[34:35], v[38:39]
	v_pk_add_f32 v[34:35], v[36:37], 1.0 op_sel_hi:[1,0]
	v_pk_fma_f32 v[136:137], v[4:5], v[20:21], v[24:25]
	v_pk_add_f32 v[20:21], v[22:23], 1.0 op_sel_hi:[1,0]
	v_pk_fma_f32 v[134:135], v[2:3], v[34:35], v[40:41]
	v_pk_fma_f32 v[138:139], v[6:7], v[20:21], v[26:27]
	v_pk_add_f32 v[20:21], v[28:29], 1.0 op_sel_hi:[1,0]
	s_nop 0
	v_pk_fma_f32 v[140:141], v[8:9], v[20:21], v[42:43]
	v_pk_add_f32 v[20:21], v[30:31], 1.0 op_sel_hi:[1,0]
	s_nop 0
	v_pk_fma_f32 v[30:31], v[10:11], v[20:21], v[44:45]
	v_add_f32_e32 v20, 1.0, v46
	v_add_f32_e32 v21, 1.0, v47
	v_fma_f32 v16, v12, v20, v16
	v_add_f32_e32 v20, 1.0, v48
	v_fmac_f32_e32 v17, v13, v21
	v_add_f32_e32 v21, 1.0, v49
	v_pk_fma_f32 v[142:143], v[14:15], v[20:21], v[18:19]
	ds_read_b32 v166, v175
	ds_read_b32 v167, v175 offset:1024
	v_readlane_b32 s0, v251, 40
	v_readlane_b32 s1, v251, 41
	v_readlane_b32 s6, v251, 42
	v_readlane_b32 s7, v251, 43
	v_readfirstlane_b32 s16, v104
	v_readfirstlane_b32 s17, v105
	v_and_b32_e32 v103, 63, v206
	v_lshlrev_b32_e32 v103, 4, v103
	v_and_b32_e32 v169, 3, v206
	v_lshl_add_u32 v169, v169, 4, v174
	s_mov_b32 s2, 0xaaaaaaaa
	s_mov_b32 s3, 0xaaaaaaaa
	s_mov_b32 s4, 0xcccccccc
	s_mov_b32 s5, 0xcccccccc
	s_waitcnt lgkmcnt(0)
	v_lshlrev_b32_e32 v166, 2, v166
	v_lshlrev_b32_e32 v167, 2, v167
	global_load_dword v26, v166, s[0:1]
	global_load_dword v27, v166, s[6:7]
	global_load_dword v28, v167, s[0:1]
	global_load_dword v29, v167, s[6:7]
	ds_read_b32 v148, v169 offset:0
	s_waitcnt lgkmcnt(0)
	v_mov_b32_dpp v182, v148 quad_perm:[0,0,0,0] row_mask:0xf bank_mask:0xf
	v_mov_b32_dpp v183, v148 quad_perm:[1,1,1,1] row_mask:0xf bank_mask:0xf
	v_mov_b32_dpp v184, v148 quad_perm:[2,2,2,2] row_mask:0xf bank_mask:0xf
	v_mov_b32_dpp v125, v148 quad_perm:[3,3,3,3] row_mask:0xf bank_mask:0xf
	v_lshl_add_u32 v182, v182, 11, v103
	v_lshl_add_u32 v183, v183, 11, v103
	v_lshl_add_u32 v184, v184, 11, v103
	v_lshl_add_u32 v125, v125, 11, v103
	global_load_dwordx4 v[34:37], v182, s[16:17]
	global_load_dwordx4 v[38:41], v182, s[16:17] offset:1024
	global_load_dwordx4 v[42:45], v183, s[16:17]
	global_load_dwordx4 v[46:49], v183, s[16:17] offset:1024
	global_load_dwordx4 v[50:53], v184, s[16:17]
	global_load_dwordx4 v[54:57], v184, s[16:17] offset:1024
	global_load_dwordx4 v[58:61], v125, s[16:17]
	global_load_dwordx4 v[62:65], v125, s[16:17] offset:1024
	ds_read_b32 v148, v169 offset:64
	s_waitcnt lgkmcnt(0)
	v_mov_b32_dpp v182, v148 quad_perm:[0,0,0,0] row_mask:0xf bank_mask:0xf
	v_mov_b32_dpp v183, v148 quad_perm:[1,1,1,1] row_mask:0xf bank_mask:0xf
	v_mov_b32_dpp v184, v148 quad_perm:[2,2,2,2] row_mask:0xf bank_mask:0xf
	v_mov_b32_dpp v125, v148 quad_perm:[3,3,3,3] row_mask:0xf bank_mask:0xf
	v_lshl_add_u32 v182, v182, 11, v103
	v_lshl_add_u32 v183, v183, 11, v103
	v_lshl_add_u32 v184, v184, 11, v103
	v_lshl_add_u32 v125, v125, 11, v103
	global_load_dwordx4 v[66:69], v182, s[16:17]
	global_load_dwordx4 v[70:73], v182, s[16:17] offset:1024
	global_load_dwordx4 v[74:77], v183, s[16:17]
	global_load_dwordx4 v[78:81], v183, s[16:17] offset:1024
	global_load_dwordx4 v[82:85], v184, s[16:17]
	global_load_dwordx4 v[86:89], v184, s[16:17] offset:1024
	global_load_dwordx4 v[90:93], v125, s[16:17]
	global_load_dwordx4 v[94:97], v125, s[16:17] offset:1024
	s_waitcnt vmcnt(16)
	ds_write_b64 v175, v[26:27] offset:8
	ds_write_b64 v175, v[28:29] offset:1032
	v_mov_b32_e32 v144, 0
	v_mov_b32_e32 v145, 0
	v_mov_b32_e32 v146, 0
	v_mov_b32_e32 v147, 0
	v_mov_b32_e32 v150, 0
	v_mov_b32_e32 v151, 0
	v_mov_b32_e32 v152, 0
	v_mov_b32_e32 v153, 0
	v_mov_b32_e32 v154, 0
	v_mov_b32_e32 v155, 0
	v_mov_b32_e32 v160, 0
	v_mov_b32_e32 v161, 0
	v_mov_b32_e32 v162, 0
	v_mov_b32_e32 v163, 0
	v_mov_b32_e32 v164, 0
	v_mov_b32_e32 v165, 0
	s_mov_b32 s10, 0
.Lex_loop:
	s_waitcnt vmcnt(8)
	ds_read_b128 v[156:159], v169 offset:0
	v_cvt_pk_f32_fp8_e32 v[18:19], v34
	v_cvt_pk_f32_fp8_e32 v[20:21], v42
	v_cvt_pk_f32_fp8_e32 v[22:23], v50
	v_cvt_pk_f32_fp8_e32 v[24:25], v58
	v_pk_mul_f32 v[26:27], v[18:19], v[132:133]
	v_pk_mul_f32 v[28:29], v[20:21], v[132:133]
	v_pk_mul_f32 v[98:99], v[22:23], v[132:133]
	v_pk_mul_f32 v[100:101], v[24:25], v[132:133]
	v_cvt_pk_f32_fp8_sdwa v[18:19], v34 src0_sel:WORD_1
	v_cvt_pk_f32_fp8_sdwa v[20:21], v42 src0_sel:WORD_1
	v_cvt_pk_f32_fp8_sdwa v[22:23], v50 src0_sel:WORD_1
	v_cvt_pk_f32_fp8_sdwa v[24:25], v58 src0_sel:WORD_1
	v_pk_fma_f32 v[26:27], v[18:19], v[134:135], v[26:27]
	v_pk_fma_f32 v[28:29], v[20:21], v[134:135], v[28:29]
	v_pk_fma_f32 v[98:99], v[22:23], v[134:135], v[98:99]
	v_pk_fma_f32 v[100:101], v[24:25], v[134:135], v[100:101]
	v_cvt_pk_f32_fp8_e32 v[18:19], v35
	v_cvt_pk_f32_fp8_e32 v[20:21], v43
	v_cvt_pk_f32_fp8_e32 v[22:23], v51
	v_cvt_pk_f32_fp8_e32 v[24:25], v59
	v_pk_fma_f32 v[26:27], v[18:19], v[136:137], v[26:27]
	v_pk_fma_f32 v[28:29], v[20:21], v[136:137], v[28:29]
	v_pk_fma_f32 v[98:99], v[22:23], v[136:137], v[98:99]
	v_pk_fma_f32 v[100:101], v[24:25], v[136:137], v[100:101]
	v_cvt_pk_f32_fp8_sdwa v[18:19], v35 src0_sel:WORD_1
	v_cvt_pk_f32_fp8_sdwa v[20:21], v43 src0_sel:WORD_1
	v_cvt_pk_f32_fp8_sdwa v[22:23], v51 src0_sel:WORD_1
	v_cvt_pk_f32_fp8_sdwa v[24:25], v59 src0_sel:WORD_1
	v_pk_fma_f32 v[26:27], v[18:19], v[138:139], v[26:27]
	v_pk_fma_f32 v[28:29], v[20:21], v[138:139], v[28:29]
	v_pk_fma_f32 v[98:99], v[22:23], v[138:139], v[98:99]
	v_pk_fma_f32 v[100:101], v[24:25], v[138:139], v[100:101]
	v_cvt_pk_f32_fp8_e32 v[18:19], v36
	v_cvt_pk_f32_fp8_e32 v[20:21], v44
	v_cvt_pk_f32_fp8_e32 v[22:23], v52
	v_cvt_pk_f32_fp8_e32 v[24:25], v60
	v_pk_fma_f32 v[26:27], v[18:19], v[140:141], v[26:27]
	v_pk_fma_f32 v[28:29], v[20:21], v[140:141], v[28:29]
	v_pk_fma_f32 v[98:99], v[22:23], v[140:141], v[98:99]
	v_pk_fma_f32 v[100:101], v[24:25], v[140:141], v[100:101]
	v_cvt_pk_f32_fp8_sdwa v[18:19], v36 src0_sel:WORD_1
	v_cvt_pk_f32_fp8_sdwa v[20:21], v44 src0_sel:WORD_1
	v_cvt_pk_f32_fp8_sdwa v[22:23], v52 src0_sel:WORD_1
	v_cvt_pk_f32_fp8_sdwa v[24:25], v60 src0_sel:WORD_1
	v_pk_fma_f32 v[26:27], v[18:19], v[30:31], v[26:27]
	v_pk_fma_f32 v[28:29], v[20:21], v[30:31], v[28:29]
	v_pk_fma_f32 v[98:99], v[22:23], v[30:31], v[98:99]
	v_pk_fma_f32 v[100:101], v[24:25], v[30:31], v[100:101]
	v_cvt_pk_f32_fp8_e32 v[18:19], v37
	v_cvt_pk_f32_fp8_e32 v[20:21], v45
	v_cvt_pk_f32_fp8_e32 v[22:23], v53
	v_cvt_pk_f32_fp8_e32 v[24:25], v61
	v_pk_fma_f32 v[26:27], v[18:19], v[16:17], v[26:27]
	v_pk_fma_f32 v[28:29], v[20:21], v[16:17], v[28:29]
	v_pk_fma_f32 v[98:99], v[22:23], v[16:17], v[98:99]
	v_pk_fma_f32 v[100:101], v[24:25], v[16:17], v[100:101]
	v_cvt_pk_f32_fp8_sdwa v[18:19], v37 src0_sel:WORD_1
	v_cvt_pk_f32_fp8_sdwa v[20:21], v45 src0_sel:WORD_1
	v_cvt_pk_f32_fp8_sdwa v[22:23], v53 src0_sel:WORD_1
	v_cvt_pk_f32_fp8_sdwa v[24:25], v61 src0_sel:WORD_1
	v_pk_fma_f32 v[26:27], v[18:19], v[142:143], v[26:27]
	v_pk_fma_f32 v[28:29], v[20:21], v[142:143], v[28:29]
	v_pk_fma_f32 v[98:99], v[22:23], v[142:143], v[98:99]
	v_pk_fma_f32 v[100:101], v[24:25], v[142:143], v[100:101]
	v_add_f32_e32 v26, v26, v27
	v_add_f32_e32 v28, v28, v29
	v_add_f32_e32 v98, v98, v99
	v_add_f32_e32 v100, v100, v101
	v_cndmask_b32_e64 v166, v26, v28, s[2:3]
	v_cndmask_b32_e64 v167, v28, v26, s[2:3]
	v_cndmask_b32_e64 v168, v98, v100, s[2:3]
	v_cndmask_b32_e64 v27, v100, v98, s[2:3]
	s_nop 0
	v_add_f32_dpp v166, v167, v166 quad_perm:[1,0,3,2] row_mask:0xf bank_mask:0xf
	v_add_f32_dpp v168, v27, v168 quad_perm:[1,0,3,2] row_mask:0xf bank_mask:0xf
	s_nop 0
	v_cndmask_b32_e64 v167, v166, v168, s[4:5]
	v_cndmask_b32_e64 v27, v168, v166, s[4:5]
	s_nop 1
	v_add_f32_dpp v167, v27, v167 quad_perm:[2,3,0,1] row_mask:0xf bank_mask:0xf
	s_nop 1
	v_add_f32_dpp v167, v167, v167 row_ror:4 row_mask:0xf bank_mask:0xf
	s_nop 1
	v_add_f32_dpp v167, v167, v167 row_ror:8 row_mask:0xf bank_mask:0xf
	v_mov_b32_e32 v166, v167
	s_nop 1
	v_permlane16_swap_b32_e32 v166, v167
	v_add_f32_e32 v167, v167, v166
	v_mov_b32_e32 v166, v167
	s_nop 1
	v_permlane32_swap_b32_e32 v166, v167
	v_add_f32_e32 v167, v167, v166
	s_waitcnt lgkmcnt(0)
	v_mul_f32_e32 v167, v158, v167
	v_mul_f32_e32 v149, v167, v167
	v_mul_f32_e32 v149, 0x3d372713, v149
	v_add_f32_e32 v149, 1.0, v149
	v_mul_f32_e32 v149, v167, v149
	v_mul_f32_e32 v149, 0xc0135761, v149
	v_exp_f32_e32 v149, v149
	v_mul_f32_e32 v255, v157, v159
	v_add_f32_e32 v149, 1.0, v149
	v_rcp_f32_e32 v149, v149
	v_mul_f32_e32 v255, v255, v167
	v_mul_f32_e32 v149, v255, v149
	s_nop 1
	v_mov_b32_dpp v170, v149 quad_perm:[0,0,0,0] row_mask:0xf bank_mask:0xf
	v_mov_b32_dpp v171, v149 quad_perm:[1,1,1,1] row_mask:0xf bank_mask:0xf
	v_mov_b32_dpp v172, v149 quad_perm:[2,2,2,2] row_mask:0xf bank_mask:0xf
	v_mov_b32_dpp v173, v149 quad_perm:[3,3,3,3] row_mask:0xf bank_mask:0xf
	v_cvt_pk_f32_fp8_e32 v[18:19], v38
	v_cvt_pk_f32_fp8_sdwa v[20:21], v38 src0_sel:WORD_1
	v_pk_fma_f32 v[144:145], v[18:19], v[170:171], v[144:145] op_sel_hi:[1,0,1]
	v_cvt_pk_f32_fp8_e32 v[22:23], v39
	v_pk_fma_f32 v[146:147], v[20:21], v[170:171], v[146:147] op_sel_hi:[1,0,1]
	v_cvt_pk_f32_fp8_sdwa v[24:25], v39 src0_sel:WORD_1
	v_pk_fma_f32 v[150:151], v[22:23], v[170:171], v[150:151] op_sel_hi:[1,0,1]
	v_cvt_pk_f32_fp8_e32 v[18:19], v40
	v_pk_fma_f32 v[152:153], v[24:25], v[170:171], v[152:153] op_sel_hi:[1,0,1]
	v_cvt_pk_f32_fp8_sdwa v[20:21], v40 src0_sel:WORD_1
	v_pk_fma_f32 v[160:161], v[18:19], v[170:171], v[160:161] op_sel_hi:[1,0,1]
	v_cvt_pk_f32_fp8_e32 v[22:23], v41
	v_pk_fma_f32 v[162:163], v[20:21], v[170:171], v[162:163] op_sel_hi:[1,0,1]
	v_cvt_pk_f32_fp8_sdwa v[24:25], v41 src0_sel:WORD_1
	v_pk_fma_f32 v[164:165], v[22:23], v[170:171], v[164:165] op_sel_hi:[1,0,1]
	v_pk_fma_f32 v[154:155], v[24:25], v[170:171], v[154:155] op_sel_hi:[1,0,1]
	v_cvt_pk_f32_fp8_e32 v[18:19], v46
	v_cvt_pk_f32_fp8_sdwa v[20:21], v46 src0_sel:WORD_1
	v_pk_fma_f32 v[144:145], v[18:19], v[170:171], v[144:145] op_sel:[0,1,0]
	v_cvt_pk_f32_fp8_e32 v[22:23], v47
	v_pk_fma_f32 v[146:147], v[20:21], v[170:171], v[146:147] op_sel:[0,1,0]
	v_cvt_pk_f32_fp8_sdwa v[24:25], v47 src0_sel:WORD_1
	v_pk_fma_f32 v[150:151], v[22:23], v[170:171], v[150:151] op_sel:[0,1,0]
	v_cvt_pk_f32_fp8_e32 v[18:19], v48
	v_pk_fma_f32 v[152:153], v[24:25], v[170:171], v[152:153] op_sel:[0,1,0]
	v_cvt_pk_f32_fp8_sdwa v[20:21], v48 src0_sel:WORD_1
	v_pk_fma_f32 v[160:161], v[18:19], v[170:171], v[160:161] op_sel:[0,1,0]
	v_cvt_pk_f32_fp8_e32 v[22:23], v49
	v_pk_fma_f32 v[162:163], v[20:21], v[170:171], v[162:163] op_sel:[0,1,0]
	v_cvt_pk_f32_fp8_sdwa v[24:25], v49 src0_sel:WORD_1
	v_pk_fma_f32 v[164:165], v[22:23], v[170:171], v[164:165] op_sel:[0,1,0]
	v_pk_fma_f32 v[154:155], v[24:25], v[170:171], v[154:155] op_sel:[0,1,0]
	v_cvt_pk_f32_fp8_e32 v[18:19], v54
	v_cvt_pk_f32_fp8_sdwa v[20:21], v54 src0_sel:WORD_1
	v_pk_fma_f32 v[144:145], v[18:19], v[172:173], v[144:145] op_sel_hi:[1,0,1]
	v_cvt_pk_f32_fp8_e32 v[22:23], v55
	v_pk_fma_f32 v[146:147], v[20:21], v[172:173], v[146:147] op_sel_hi:[1,0,1]
	v_cvt_pk_f32_fp8_sdwa v[24:25], v55 src0_sel:WORD_1
	v_pk_fma_f32 v[150:151], v[22:23], v[172:173], v[150:151] op_sel_hi:[1,0,1]
	v_cvt_pk_f32_fp8_e32 v[18:19], v56
	v_pk_fma_f32 v[152:153], v[24:25], v[172:173], v[152:153] op_sel_hi:[1,0,1]
	v_cvt_pk_f32_fp8_sdwa v[20:21], v56 src0_sel:WORD_1
	v_pk_fma_f32 v[160:161], v[18:19], v[172:173], v[160:161] op_sel_hi:[1,0,1]
	v_cvt_pk_f32_fp8_e32 v[22:23], v57
	v_pk_fma_f32 v[162:163], v[20:21], v[172:173], v[162:163] op_sel_hi:[1,0,1]
	v_cvt_pk_f32_fp8_sdwa v[24:25], v57 src0_sel:WORD_1
	v_pk_fma_f32 v[164:165], v[22:23], v[172:173], v[164:165] op_sel_hi:[1,0,1]
	v_pk_fma_f32 v[154:155], v[24:25], v[172:173], v[154:155] op_sel_hi:[1,0,1]
	v_cvt_pk_f32_fp8_e32 v[18:19], v62
	v_cvt_pk_f32_fp8_sdwa v[20:21], v62 src0_sel:WORD_1
	v_pk_fma_f32 v[144:145], v[18:19], v[172:173], v[144:145] op_sel:[0,1,0]
	v_cvt_pk_f32_fp8_e32 v[22:23], v63
	v_pk_fma_f32 v[146:147], v[20:21], v[172:173], v[146:147] op_sel:[0,1,0]
	v_cvt_pk_f32_fp8_sdwa v[24:25], v63 src0_sel:WORD_1
	v_pk_fma_f32 v[150:151], v[22:23], v[172:173], v[150:151] op_sel:[0,1,0]
	v_cvt_pk_f32_fp8_e32 v[18:19], v64
	v_pk_fma_f32 v[152:153], v[24:25], v[172:173], v[152:153] op_sel:[0,1,0]
	v_cvt_pk_f32_fp8_sdwa v[20:21], v64 src0_sel:WORD_1
	v_pk_fma_f32 v[160:161], v[18:19], v[172:173], v[160:161] op_sel:[0,1,0]
	v_cvt_pk_f32_fp8_e32 v[22:23], v65
	v_pk_fma_f32 v[162:163], v[20:21], v[172:173], v[162:163] op_sel:[0,1,0]
	v_cvt_pk_f32_fp8_sdwa v[24:25], v65 src0_sel:WORD_1
	v_pk_fma_f32 v[164:165], v[22:23], v[172:173], v[164:165] op_sel:[0,1,0]
	v_pk_fma_f32 v[154:155], v[24:25], v[172:173], v[154:155] op_sel:[0,1,0]
	s_cmp_eq_u32 s10, 15
	s_cbranch_scc1 .Lex_lastB
	ds_read_b32 v148, v169 offset:128
	s_waitcnt lgkmcnt(0)
	v_mov_b32_dpp v182, v148 quad_perm:[0,0,0,0] row_mask:0xf bank_mask:0xf
	v_mov_b32_dpp v183, v148 quad_perm:[1,1,1,1] row_mask:0xf bank_mask:0xf
	v_mov_b32_dpp v184, v148 quad_perm:[2,2,2,2] row_mask:0xf bank_mask:0xf
	v_mov_b32_dpp v125, v148 quad_perm:[3,3,3,3] row_mask:0xf bank_mask:0xf
	v_lshl_add_u32 v182, v182, 11, v103
	v_lshl_add_u32 v183, v183, 11, v103
	v_lshl_add_u32 v184, v184, 11, v103
	v_lshl_add_u32 v125, v125, 11, v103
	global_load_dwordx4 v[34:37], v182, s[16:17]
	global_load_dwordx4 v[38:41], v182, s[16:17] offset:1024
	global_load_dwordx4 v[42:45], v183, s[16:17]
	global_load_dwordx4 v[46:49], v183, s[16:17] offset:1024
	global_load_dwordx4 v[50:53], v184, s[16:17]
	global_load_dwordx4 v[54:57], v184, s[16:17] offset:1024
	global_load_dwordx4 v[58:61], v125, s[16:17]
	global_load_dwordx4 v[62:65], v125, s[16:17] offset:1024
	s_waitcnt vmcnt(8)
	s_branch .Lex_goB

.Lex_goB:
	ds_read_b128 v[156:159], v169 offset:64
	v_cvt_pk_f32_fp8_e32 v[18:19], v66
	v_cvt_pk_f32_fp8_e32 v[20:21], v74
	v_cvt_pk_f32_fp8_e32 v[22:23], v82
	v_cvt_pk_f32_fp8_e32 v[24:25], v90
	v_pk_mul_f32 v[26:27], v[18:19], v[132:133]
	v_pk_mul_f32 v[28:29], v[20:21], v[132:133]
	v_pk_mul_f32 v[98:99], v[22:23], v[132:133]
	v_pk_mul_f32 v[100:101], v[24:25], v[132:133]
	v_cvt_pk_f32_fp8_sdwa v[18:19], v66 src0_sel:WORD_1
	v_cvt_pk_f32_fp8_sdwa v[20:21], v74 src0_sel:WORD_1
	v_cvt_pk_f32_fp8_sdwa v[22:23], v82 src0_sel:WORD_1
	v_cvt_pk_f32_fp8_sdwa v[24:25], v90 src0_sel:WORD_1
	v_pk_fma_f32 v[26:27], v[18:19], v[134:135], v[26:27]
	v_pk_fma_f32 v[28:29], v[20:21], v[134:135], v[28:29]
	v_pk_fma_f32 v[98:99], v[22:23], v[134:135], v[98:99]
	v_pk_fma_f32 v[100:101], v[24:25], v[134:135], v[100:101]
	v_cvt_pk_f32_fp8_e32 v[18:19], v67
	v_cvt_pk_f32_fp8_e32 v[20:21], v75
	v_cvt_pk_f32_fp8_e32 v[22:23], v83
	v_cvt_pk_f32_fp8_e32 v[24:25], v91
	v_pk_fma_f32 v[26:27], v[18:19], v[136:137], v[26:27]
	v_pk_fma_f32 v[28:29], v[20:21], v[136:137], v[28:29]
	v_pk_fma_f32 v[98:99], v[22:23], v[136:137], v[98:99]
	v_pk_fma_f32 v[100:101], v[24:25], v[136:137], v[100:101]
	v_cvt_pk_f32_fp8_sdwa v[18:19], v67 src0_sel:WORD_1
	v_cvt_pk_f32_fp8_sdwa v[20:21], v75 src0_sel:WORD_1
	v_cvt_pk_f32_fp8_sdwa v[22:23], v83 src0_sel:WORD_1
	v_cvt_pk_f32_fp8_sdwa v[24:25], v91 src0_sel:WORD_1
	v_pk_fma_f32 v[26:27], v[18:19], v[138:139], v[26:27]
	v_pk_fma_f32 v[28:29], v[20:21], v[138:139], v[28:29]
	v_pk_fma_f32 v[98:99], v[22:23], v[138:139], v[98:99]
	v_pk_fma_f32 v[100:101], v[24:25], v[138:139], v[100:101]
	v_cvt_pk_f32_fp8_e32 v[18:19], v68
	v_cvt_pk_f32_fp8_e32 v[20:21], v76
	v_cvt_pk_f32_fp8_e32 v[22:23], v84
	v_cvt_pk_f32_fp8_e32 v[24:25], v92
	v_pk_fma_f32 v[26:27], v[18:19], v[140:141], v[26:27]
	v_pk_fma_f32 v[28:29], v[20:21], v[140:141], v[28:29]
	v_pk_fma_f32 v[98:99], v[22:23], v[140:141], v[98:99]
	v_pk_fma_f32 v[100:101], v[24:25], v[140:141], v[100:101]
	v_cvt_pk_f32_fp8_sdwa v[18:19], v68 src0_sel:WORD_1
	v_cvt_pk_f32_fp8_sdwa v[20:21], v76 src0_sel:WORD_1
	v_cvt_pk_f32_fp8_sdwa v[22:23], v84 src0_sel:WORD_1
	v_cvt_pk_f32_fp8_sdwa v[24:25], v92 src0_sel:WORD_1
	v_pk_fma_f32 v[26:27], v[18:19], v[30:31], v[26:27]
	v_pk_fma_f32 v[28:29], v[20:21], v[30:31], v[28:29]
	v_pk_fma_f32 v[98:99], v[22:23], v[30:31], v[98:99]
	v_pk_fma_f32 v[100:101], v[24:25], v[30:31], v[100:101]
	v_cvt_pk_f32_fp8_e32 v[18:19], v69
	v_cvt_pk_f32_fp8_e32 v[20:21], v77
	v_cvt_pk_f32_fp8_e32 v[22:23], v85
	v_cvt_pk_f32_fp8_e32 v[24:25], v93
	v_pk_fma_f32 v[26:27], v[18:19], v[16:17], v[26:27]
	v_pk_fma_f32 v[28:29], v[20:21], v[16:17], v[28:29]
	v_pk_fma_f32 v[98:99], v[22:23], v[16:17], v[98:99]
	v_pk_fma_f32 v[100:101], v[24:25], v[16:17], v[100:101]
	v_cvt_pk_f32_fp8_sdwa v[18:19], v69 src0_sel:WORD_1
	v_cvt_pk_f32_fp8_sdwa v[20:21], v77 src0_sel:WORD_1
	v_cvt_pk_f32_fp8_sdwa v[22:23], v85 src0_sel:WORD_1
	v_cvt_pk_f32_fp8_sdwa v[24:25], v93 src0_sel:WORD_1
	v_pk_fma_f32 v[26:27], v[18:19], v[142:143], v[26:27]
	v_pk_fma_f32 v[28:29], v[20:21], v[142:143], v[28:29]
	v_pk_fma_f32 v[98:99], v[22:23], v[142:143], v[98:99]
	v_pk_fma_f32 v[100:101], v[24:25], v[142:143], v[100:101]
	v_add_f32_e32 v26, v26, v27
	v_add_f32_e32 v28, v28, v29
	v_add_f32_e32 v98, v98, v99
	v_add_f32_e32 v100, v100, v101
	v_cndmask_b32_e64 v166, v26, v28, s[2:3]
	v_cndmask_b32_e64 v167, v28, v26, s[2:3]
	v_cndmask_b32_e64 v168, v98, v100, s[2:3]
	v_cndmask_b32_e64 v27, v100, v98, s[2:3]
	s_nop 0
	v_add_f32_dpp v166, v167, v166 quad_perm:[1,0,3,2] row_mask:0xf bank_mask:0xf
	v_add_f32_dpp v168, v27, v168 quad_perm:[1,0,3,2] row_mask:0xf bank_mask:0xf
	s_nop 0
	v_cndmask_b32_e64 v167, v166, v168, s[4:5]
	v_cndmask_b32_e64 v27, v168, v166, s[4:5]
	s_nop 1
	v_add_f32_dpp v167, v27, v167 quad_perm:[2,3,0,1] row_mask:0xf bank_mask:0xf
	s_nop 1
	v_add_f32_dpp v167, v167, v167 row_ror:4 row_mask:0xf bank_mask:0xf
	s_nop 1
	v_add_f32_dpp v167, v167, v167 row_ror:8 row_mask:0xf bank_mask:0xf
	v_mov_b32_e32 v166, v167
	s_nop 1
	v_permlane16_swap_b32_e32 v166, v167
	v_add_f32_e32 v167, v167, v166
	v_mov_b32_e32 v166, v167
	s_nop 1
	v_permlane32_swap_b32_e32 v166, v167
	v_add_f32_e32 v167, v167, v166
	s_waitcnt lgkmcnt(0)
	v_mul_f32_e32 v167, v158, v167
	v_mul_f32_e32 v149, v167, v167
	v_mul_f32_e32 v149, 0x3d372713, v149
	v_add_f32_e32 v149, 1.0, v149
	v_mul_f32_e32 v149, v167, v149
	v_mul_f32_e32 v149, 0xc0135761, v149
	v_exp_f32_e32 v149, v149
	v_mul_f32_e32 v255, v157, v159
	v_add_f32_e32 v149, 1.0, v149
	v_rcp_f32_e32 v149, v149
	v_mul_f32_e32 v255, v255, v167
	v_mul_f32_e32 v149, v255, v149
	s_nop 1
	v_mov_b32_dpp v170, v149 quad_perm:[0,0,0,0] row_mask:0xf bank_mask:0xf
	v_mov_b32_dpp v171, v149 quad_perm:[1,1,1,1] row_mask:0xf bank_mask:0xf
	v_mov_b32_dpp v172, v149 quad_perm:[2,2,2,2] row_mask:0xf bank_mask:0xf
	v_mov_b32_dpp v173, v149 quad_perm:[3,3,3,3] row_mask:0xf bank_mask:0xf
	v_cvt_pk_f32_fp8_e32 v[18:19], v70
	v_cvt_pk_f32_fp8_sdwa v[20:21], v70 src0_sel:WORD_1
	v_pk_fma_f32 v[144:145], v[18:19], v[170:171], v[144:145] op_sel_hi:[1,0,1]
	v_cvt_pk_f32_fp8_e32 v[22:23], v71
	v_pk_fma_f32 v[146:147], v[20:21], v[170:171], v[146:147] op_sel_hi:[1,0,1]
	v_cvt_pk_f32_fp8_sdwa v[24:25], v71 src0_sel:WORD_1
	v_pk_fma_f32 v[150:151], v[22:23], v[170:171], v[150:151] op_sel_hi:[1,0,1]
	v_cvt_pk_f32_fp8_e32 v[18:19], v72
	v_pk_fma_f32 v[152:153], v[24:25], v[170:171], v[152:153] op_sel_hi:[1,0,1]
	v_cvt_pk_f32_fp8_sdwa v[20:21], v72 src0_sel:WORD_1
	v_pk_fma_f32 v[160:161], v[18:19], v[170:171], v[160:161] op_sel_hi:[1,0,1]
	v_cvt_pk_f32_fp8_e32 v[22:23], v73
	v_pk_fma_f32 v[162:163], v[20:21], v[170:171], v[162:163] op_sel_hi:[1,0,1]
	v_cvt_pk_f32_fp8_sdwa v[24:25], v73 src0_sel:WORD_1
	v_pk_fma_f32 v[164:165], v[22:23], v[170:171], v[164:165] op_sel_hi:[1,0,1]
	v_pk_fma_f32 v[154:155], v[24:25], v[170:171], v[154:155] op_sel_hi:[1,0,1]
	v_cvt_pk_f32_fp8_e32 v[18:19], v78
	v_cvt_pk_f32_fp8_sdwa v[20:21], v78 src0_sel:WORD_1
	v_pk_fma_f32 v[144:145], v[18:19], v[170:171], v[144:145] op_sel:[0,1,0]
	v_cvt_pk_f32_fp8_e32 v[22:23], v79
	v_pk_fma_f32 v[146:147], v[20:21], v[170:171], v[146:147] op_sel:[0,1,0]
	v_cvt_pk_f32_fp8_sdwa v[24:25], v79 src0_sel:WORD_1
	v_pk_fma_f32 v[150:151], v[22:23], v[170:171], v[150:151] op_sel:[0,1,0]
	v_cvt_pk_f32_fp8_e32 v[18:19], v80
	v_pk_fma_f32 v[152:153], v[24:25], v[170:171], v[152:153] op_sel:[0,1,0]
	v_cvt_pk_f32_fp8_sdwa v[20:21], v80 src0_sel:WORD_1
	v_pk_fma_f32 v[160:161], v[18:19], v[170:171], v[160:161] op_sel:[0,1,0]
	v_cvt_pk_f32_fp8_e32 v[22:23], v81
	v_pk_fma_f32 v[162:163], v[20:21], v[170:171], v[162:163] op_sel:[0,1,0]
	v_cvt_pk_f32_fp8_sdwa v[24:25], v81 src0_sel:WORD_1
	v_pk_fma_f32 v[164:165], v[22:23], v[170:171], v[164:165] op_sel:[0,1,0]
	v_pk_fma_f32 v[154:155], v[24:25], v[170:171], v[154:155] op_sel:[0,1,0]
	v_cvt_pk_f32_fp8_e32 v[18:19], v86
	v_cvt_pk_f32_fp8_sdwa v[20:21], v86 src0_sel:WORD_1
	v_pk_fma_f32 v[144:145], v[18:19], v[172:173], v[144:145] op_sel_hi:[1,0,1]
	v_cvt_pk_f32_fp8_e32 v[22:23], v87
	v_pk_fma_f32 v[146:147], v[20:21], v[172:173], v[146:147] op_sel_hi:[1,0,1]
	v_cvt_pk_f32_fp8_sdwa v[24:25], v87 src0_sel:WORD_1
	v_pk_fma_f32 v[150:151], v[22:23], v[172:173], v[150:151] op_sel_hi:[1,0,1]
	v_cvt_pk_f32_fp8_e32 v[18:19], v88
	v_pk_fma_f32 v[152:153], v[24:25], v[172:173], v[152:153] op_sel_hi:[1,0,1]
	v_cvt_pk_f32_fp8_sdwa v[20:21], v88 src0_sel:WORD_1
	v_pk_fma_f32 v[160:161], v[18:19], v[172:173], v[160:161] op_sel_hi:[1,0,1]
	v_cvt_pk_f32_fp8_e32 v[22:23], v89
	v_pk_fma_f32 v[162:163], v[20:21], v[172:173], v[162:163] op_sel_hi:[1,0,1]
	v_cvt_pk_f32_fp8_sdwa v[24:25], v89 src0_sel:WORD_1
	v_pk_fma_f32 v[164:165], v[22:23], v[172:173], v[164:165] op_sel_hi:[1,0,1]
	v_pk_fma_f32 v[154:155], v[24:25], v[172:173], v[154:155] op_sel_hi:[1,0,1]
	v_cvt_pk_f32_fp8_e32 v[18:19], v94
	v_cvt_pk_f32_fp8_sdwa v[20:21], v94 src0_sel:WORD_1
	v_pk_fma_f32 v[144:145], v[18:19], v[172:173], v[144:145] op_sel:[0,1,0]
	v_cvt_pk_f32_fp8_e32 v[22:23], v95
	v_pk_fma_f32 v[146:147], v[20:21], v[172:173], v[146:147] op_sel:[0,1,0]
	v_cvt_pk_f32_fp8_sdwa v[24:25], v95 src0_sel:WORD_1
	v_pk_fma_f32 v[150:151], v[22:23], v[172:173], v[150:151] op_sel:[0,1,0]
	v_cvt_pk_f32_fp8_e32 v[18:19], v96
	v_pk_fma_f32 v[152:153], v[24:25], v[172:173], v[152:153] op_sel:[0,1,0]
	v_cvt_pk_f32_fp8_sdwa v[20:21], v96 src0_sel:WORD_1
	v_pk_fma_f32 v[160:161], v[18:19], v[172:173], v[160:161] op_sel:[0,1,0]
	v_cvt_pk_f32_fp8_e32 v[22:23], v97
	v_pk_fma_f32 v[162:163], v[20:21], v[172:173], v[162:163] op_sel:[0,1,0]
	v_cvt_pk_f32_fp8_sdwa v[24:25], v97 src0_sel:WORD_1
	v_pk_fma_f32 v[164:165], v[22:23], v[172:173], v[164:165] op_sel:[0,1,0]
	v_pk_fma_f32 v[154:155], v[24:25], v[172:173], v[154:155] op_sel:[0,1,0]
	s_cmp_eq_u32 s10, 15
	s_cbranch_scc1 .Lex_done
	ds_read_b32 v148, v169 offset:192
	s_waitcnt lgkmcnt(0)
	v_mov_b32_dpp v182, v148 quad_perm:[0,0,0,0] row_mask:0xf bank_mask:0xf
	v_mov_b32_dpp v183, v148 quad_perm:[1,1,1,1] row_mask:0xf bank_mask:0xf
	v_mov_b32_dpp v184, v148 quad_perm:[2,2,2,2] row_mask:0xf bank_mask:0xf
	v_mov_b32_dpp v125, v148 quad_perm:[3,3,3,3] row_mask:0xf bank_mask:0xf
	v_lshl_add_u32 v182, v182, 11, v103
	v_lshl_add_u32 v183, v183, 11, v103
	v_lshl_add_u32 v184, v184, 11, v103
	v_lshl_add_u32 v125, v125, 11, v103
	global_load_dwordx4 v[66:69], v182, s[16:17]
	global_load_dwordx4 v[70:73], v182, s[16:17] offset:1024
	global_load_dwordx4 v[74:77], v183, s[16:17]
	global_load_dwordx4 v[78:81], v183, s[16:17] offset:1024
	global_load_dwordx4 v[82:85], v184, s[16:17]
	global_load_dwordx4 v[86:89], v184, s[16:17] offset:1024
	global_load_dwordx4 v[90:93], v125, s[16:17]
	global_load_dwordx4 v[94:97], v125, s[16:17] offset:1024
	v_add_u32_e32 v169, 0x80, v169
	s_add_u32 s10, s10, 1
	s_branch .Lex_loop
.Lex_done:
.LBB0_1948:
	s_mov_b64 s[0:1], 0x5000
	v_add_co_u32_e32 v16, vcc, 0x5000, v130
	v_lshl_add_u64 v[20:21], v[130:131], 0, s[0:1]
	s_nop 0
	v_addc_co_u32_e32 v17, vcc, 0, v131, vcc
	global_load_dwordx4 v[16:19], v[16:17], off
	s_nop 0
	global_load_dwordx4 v[20:23], v[20:21], off offset:16
	s_mov_b32 s16, 0x3fd744fd
	v_lshl_add_u64 v[24:25], v[128:129], 0, s[0:1]
	v_readlane_b32 s0, v251, 45
	v_mov_b32_e32 v125, v33
	s_waitcnt vmcnt(0)
	v_pk_mul_f32 v[22:23], v[154:155], v[22:23]
	s_nop 0
	v_pk_fma_f32 v[38:39], v[14:15], s[16:17], v[22:23] op_sel_hi:[1,0,1]
	v_pk_mul_f32 v[14:15], v[164:165], v[20:21]
	s_nop 0
	v_pk_fma_f32 v[40:41], v[12:13], s[16:17], v[14:15] op_sel_hi:[1,0,1]
	v_pk_mul_f32 v[12:13], v[162:163], v[18:19]
	s_nop 0
	v_pk_fma_f32 v[50:51], v[10:11], s[16:17], v[12:13] op_sel_hi:[1,0,1]
	v_pk_mul_f32 v[10:11], v[160:161], v[16:17]
	s_nop 0
	v_pk_fma_f32 v[52:53], v[8:9], s[16:17], v[10:11] op_sel_hi:[1,0,1]
	v_add_u32_e32 v8, s0, v123
	v_mul_i32_i24_e32 v8, 0x1800, v8
	v_readlane_b32 s0, v248, 46
	v_ashrrev_i32_e32 v9, 31, v8
	v_readlane_b32 s4, v248, 50
	v_readlane_b32 s5, v248, 51
	s_movk_i32 s0, 0x5000
	v_readlane_b32 s6, v248, 52
	v_lshl_add_u64 v[46:47], v[8:9], 2, s[4:5]
	v_lshlrev_b32_e32 v8, 11, v123
	v_readlane_b32 s7, v248, 53
	v_ashrrev_i32_e32 v9, 31, v8
	v_mov_b32_e32 v123, v33
	v_add_co_u32_e32 v26, vcc, s0, v128
	v_lshl_add_u64 v[48:49], v[8:9], 2, s[6:7]
	v_lshl_add_u64 v[8:9], v[46:47], 0, v[122:123]
	v_addc_co_u32_e32 v27, vcc, 0, v129, vcc
	v_lshl_add_u64 v[44:45], v[46:47], 0, v[124:125]
	global_load_dwordx4 v[16:19], v[8:9], off offset:16
	s_nop 0
	global_load_dwordx4 v[8:11], v[8:9], off
	s_nop 0
	global_load_dwordx4 v[20:23], v[44:45], off offset:16
	global_load_dwordx4 v[12:15], v[44:45], off
	global_load_dwordx4 v[54:57], v[26:27], off
	s_nop 0
	global_load_dwordx4 v[24:27], v[24:25], off offset:16
	v_lshl_add_u64 v[28:29], v[48:49], 0, v[122:123]
	v_lshl_add_u64 v[42:43], v[48:49], 0, v[124:125]
	v_readlane_b32 s2, v248, 48
	v_readlane_b32 s3, v248, 49
	v_readlane_b32 s1, v248, 47
	v_readlane_b32 s8, v248, 54
	v_readlane_b32 s9, v248, 55
	v_readlane_b32 s10, v248, 56
	v_readlane_b32 s11, v248, 57
	v_readlane_b32 s12, v248, 58
	v_readlane_b32 s13, v248, 59
	v_readlane_b32 s14, v248, 60
	v_readlane_b32 s15, v248, 61
	s_waitcnt vmcnt(1)
	v_pk_mul_f32 v[54:55], v[144:145], v[54:55]
	s_waitcnt vmcnt(0)
	v_pk_mul_f32 v[26:27], v[152:153], v[26:27]
	v_pk_fma_f32 v[0:1], v[0:1], s[16:17], v[54:55] op_sel_hi:[1,0,1]
	v_pk_fma_f32 v[58:59], v[6:7], s[16:17], v[26:27] op_sel_hi:[1,0,1]
	v_pk_mul_f32 v[6:7], v[150:151], v[24:25]
	v_pk_mul_f32 v[56:57], v[146:147], v[56:57]
	v_pk_fma_f32 v[76:77], v[4:5], s[16:17], v[6:7] op_sel_hi:[1,0,1]
	global_load_dwordx4 v[60:63], v[106:107], off offset:16
	global_load_dwordx4 v[64:67], v[106:107], off
	global_load_dwordx4 v[68:71], v[108:109], off offset:16
	global_load_dwordx4 v[72:75], v[108:109], off
	global_load_dwordx4 v[4:7], v[28:29], off offset:16
	global_load_dwordx4 v[34:37], v[28:29], off
	global_load_dwordx4 v[24:27], v[42:43], off offset:16
	s_nop 0
	global_load_dwordx4 v[28:31], v[42:43], off
	v_add_f32_e32 v54, 0, v0
	v_pk_fma_f32 v[2:3], v[2:3], s[16:17], v[56:57] op_sel_hi:[1,0,1]
	v_add_f32_e32 v54, v54, v1
	v_add_f32_e32 v54, v54, v2
	v_add_f32_e32 v54, v54, v3
	v_add_f32_e32 v54, v54, v76
	v_add_f32_e32 v54, v54, v77
	v_add_f32_e32 v54, v54, v58
	v_add_f32_e32 v54, v54, v59
	v_add_f32_e32 v54, v54, v52
	v_add_f32_e32 v54, v54, v53
	v_add_f32_e32 v54, v54, v50
	v_add_f32_e32 v54, v54, v51
	v_add_f32_e32 v54, v54, v40
	v_add_f32_e32 v54, v54, v41
	v_add_f32_e32 v54, v54, v38
	v_add_f32_e32 v54, v54, v39
	v_readlane_b32 s16, v253, 24
	v_readlane_b32 s17, v253, 25
	v_add_f32_dpp v54, v54, v54 quad_perm:[1,0,3,2] row_mask:0xf bank_mask:0xf bound_ctrl:1
	s_nop 1
	v_add_f32_dpp v54, v54, v54 quad_perm:[2,3,0,1] row_mask:0xf bank_mask:0xf bound_ctrl:1
	s_nop 1
	v_add_f32_dpp v54, v54, v54 row_half_mirror row_mask:0xf bank_mask:0xf bound_ctrl:1
	s_nop 1
	v_add_f32_dpp v54, v54, v54 row_mirror row_mask:0xf bank_mask:0xf bound_ctrl:1
	s_nop 0
	v_readlane_b32 s2, v54, 16
	v_readlane_b32 s3, v54, 48
	v_readlane_b32 s0, v54, 0
	v_readlane_b32 s1, v54, 32
	v_mov_b32_e32 v54, s2
	v_mov_b32_e32 v55, s3
	v_pk_add_f32 v[54:55], s[0:1], v[54:55]
	s_nop 0
	v_add_f32_e32 v54, v54, v55
	v_mul_f32_e32 v56, 0x3a800000, v54
	v_pk_add_f32 v[0:1], v[0:1], v[56:57] op_sel_hi:[1,0] neg_lo:[0,1] neg_hi:[0,1]
	v_pk_add_f32 v[2:3], v[2:3], v[56:57] op_sel_hi:[1,0] neg_lo:[0,1] neg_hi:[0,1]
	v_pk_mul_f32 v[78:79], v[0:1], v[0:1]
	v_pk_mul_f32 v[80:81], v[2:3], v[2:3]
	v_add_f32_e32 v78, v78, v79
	v_pk_add_f32 v[76:77], v[76:77], v[56:57] op_sel_hi:[1,0] neg_lo:[0,1] neg_hi:[0,1]
	v_add_f32_e32 v78, v80, v78
	v_pk_mul_f32 v[82:83], v[76:77], v[76:77]
	v_add_f32_e32 v78, v81, v78
	v_pk_add_f32 v[84:85], v[58:59], v[56:57] op_sel_hi:[1,0] neg_lo:[0,1] neg_hi:[0,1]
	v_add_f32_e32 v78, v82, v78
	v_pk_mul_f32 v[58:59], v[84:85], v[84:85]
	v_add_f32_e32 v78, v83, v78
	v_pk_add_f32 v[52:53], v[52:53], v[56:57] op_sel_hi:[1,0] neg_lo:[0,1] neg_hi:[0,1]
	v_add_f32_e32 v58, v58, v78
	v_pk_mul_f32 v[86:87], v[52:53], v[52:53]
	v_add_f32_e32 v58, v59, v58
	v_pk_add_f32 v[50:51], v[50:51], v[56:57] op_sel_hi:[1,0] neg_lo:[0,1] neg_hi:[0,1]
	v_add_f32_e32 v58, v86, v58
	v_pk_mul_f32 v[88:89], v[50:51], v[50:51]
	v_add_f32_e32 v58, v87, v58
	v_pk_add_f32 v[54:55], v[40:41], v[56:57] op_sel_hi:[1,0] neg_lo:[0,1] neg_hi:[0,1]
	v_add_f32_e32 v58, v88, v58
	v_pk_mul_f32 v[40:41], v[54:55], v[54:55]
	v_add_f32_e32 v58, v89, v58
	v_pk_add_f32 v[56:57], v[38:39], v[56:57] op_sel_hi:[1,0] neg_lo:[0,1] neg_hi:[0,1]
	v_add_f32_e32 v40, v40, v58
	v_pk_mul_f32 v[38:39], v[56:57], v[56:57]
	v_add_f32_e32 v40, v41, v40
	v_add_f32_e32 v38, v38, v40
	v_add_f32_e32 v38, v39, v38
	s_nop 1
	v_add_f32_dpp v38, v38, v38 quad_perm:[1,0,3,2] row_mask:0xf bank_mask:0xf bound_ctrl:1
	s_nop 1
	v_add_f32_dpp v38, v38, v38 quad_perm:[2,3,0,1] row_mask:0xf bank_mask:0xf bound_ctrl:1
	s_nop 1
	v_add_f32_dpp v38, v38, v38 row_half_mirror row_mask:0xf bank_mask:0xf bound_ctrl:1
	s_nop 1
	v_add_f32_dpp v38, v38, v38 row_mirror row_mask:0xf bank_mask:0xf bound_ctrl:1
	s_nop 0
	v_readlane_b32 s2, v38, 16
	v_readlane_b32 s3, v38, 48
	v_readlane_b32 s0, v38, 0
	v_readlane_b32 s1, v38, 32
	v_mov_b32_e32 v38, s2
	v_mov_b32_e32 v39, s3
	v_pk_add_f32 v[38:39], s[0:1], v[38:39]
	s_mov_b32 s0, 0x800000
	v_add_f32_e32 v38, v38, v39
	v_fmamk_f32 v38, v38, 0x3a800000, v212
	v_cmp_gt_f32_e32 vcc, s0, v38
	v_mul_f32_e32 v39, 0x4b800000, v38
	s_nop 0
	v_cndmask_b32_e32 v38, v38, v39, vcc
	v_rsq_f32_e32 v38, v38
	s_nop 0
	v_mul_f32_e32 v39, 0x45800000, v38
	v_cndmask_b32_e32 v58, v38, v39, vcc
	v_pk_mul_f32 v[0:1], v[0:1], v[58:59] op_sel_hi:[1,0]
	v_pk_mul_f32 v[2:3], v[2:3], v[58:59] op_sel_hi:[1,0]
	v_pk_mul_f32 v[38:39], v[76:77], v[58:59] op_sel_hi:[1,0]
	v_pk_mul_f32 v[40:41], v[84:85], v[58:59] op_sel_hi:[1,0]
	s_waitcnt vmcnt(4)
	v_pk_fma_f32 v[0:1], v[64:65], v[0:1], v[72:73]
	v_pk_fma_f32 v[2:3], v[2:3], v[66:67], v[74:75]
	v_pk_fma_f32 v[38:39], v[38:39], v[60:61], v[68:69]
	v_pk_fma_f32 v[40:41], v[40:41], v[62:63], v[70:71]
	v_lshl_add_u64 v[60:61], v[126:127], 2, v[110:111]
	s_and_b64 vcc, exec, s[16:17]
	v_lshl_add_u64 v[62:63], v[126:127], 1, v[116:117]
	global_store_dwordx4 v[60:61], v[0:3], off
	global_store_dwordx4 v[60:61], v[38:41], off offset:16
	s_cbranch_vccz .LBB0_1950
	v_pk_add_f32 v[18:19], v[18:19], 1.0 op_sel_hi:[1,0]
	v_pk_add_f32 v[16:17], v[16:17], 1.0 op_sel_hi:[1,0]
	v_pk_add_f32 v[10:11], v[10:11], 1.0 op_sel_hi:[1,0]
	v_pk_add_f32 v[8:9], v[8:9], 1.0 op_sel_hi:[1,0]
	v_pk_fma_f32 v[18:19], v[40:41], v[18:19], v[22:23]
	v_pk_fma_f32 v[16:17], v[38:39], v[16:17], v[20:21]
	v_pk_fma_f32 v[10:11], v[2:3], v[10:11], v[14:15]
	v_pk_fma_f32 v[8:9], v[8:9], v[0:1], v[12:13]
	s_nop 0
	v_cvt_pk_bf16_f32 v8, v8, v9
	v_cvt_pk_bf16_f32 v9, v10, v11
	v_cvt_pk_bf16_f32 v10, v16, v17
	v_cvt_pk_bf16_f32 v11, v18, v19
	global_store_dwordx4 v[62:63], v[8:11], off

	.amdhsa_kernel _Z2mk1Pii
		.amdhsa_group_segment_fixed_size 73744
		.amdhsa_private_segment_fixed_size 0
		.amdhsa_kernarg_size 744
		.amdhsa_user_sgpr_count 2
		.amdhsa_user_sgpr_dispatch_ptr 0
		.amdhsa_user_sgpr_queue_ptr 0
		.amdhsa_user_sgpr_kernarg_segment_ptr 1
		.amdhsa_user_sgpr_dispatch_id 0
		.amdhsa_user_sgpr_kernarg_preload_length 0
		.amdhsa_user_sgpr_kernarg_preload_offset 0
		.amdhsa_user_sgpr_private_segment_size 0
		.amdhsa_uses_dynamic_stack 0
		.amdhsa_enable_private_segment 0
		.amdhsa_system_sgpr_workgroup_id_x 1
		.amdhsa_system_sgpr_workgroup_id_y 0
		.amdhsa_system_sgpr_workgroup_id_z 0
		.amdhsa_system_sgpr_workgroup_info 0
		.amdhsa_system_vgpr_workitem_id 2
		.amdhsa_next_free_vgpr 256
		.amdhsa_next_free_sgpr 102
		.amdhsa_accum_offset 256
		.amdhsa_reserve_vcc 1
		.amdhsa_float_round_mode_32 0
		.amdhsa_float_round_mode_16_64 0
		.amdhsa_float_denorm_mode_32 3
		.amdhsa_float_denorm_mode_16_64 3
		.amdhsa_dx10_clamp 1
		.amdhsa_ieee_mode 1
		.amdhsa_fp16_overflow 0
		.amdhsa_tg_split 0
		.amdhsa_exception_fp_ieee_invalid_op 0
		.amdhsa_exception_fp_denorm_src 0
		.amdhsa_exception_fp_ieee_div_zero 0
		.amdhsa_exception_fp_ieee_overflow 0
		.amdhsa_exception_fp_ieee_underflow 0
		.amdhsa_exception_fp_ieee_inexact 0
		.amdhsa_exception_int_div_zero 0
	.end_amdhsa_kernel

amdhsa.kernels:
  - .agpr_count:     0
    .args:
      - .offset:         0
        .size:           480
        .value_kind:     by_value
      - .offset:         480
        .size:           4
        .value_kind:     by_value
      - .offset:         484
        .size:           4
        .value_kind:     by_value
      - .offset:         488
        .size:           4
        .value_kind:     hidden_block_count_x
      - .offset:         492
        .size:           4
        .value_kind:     hidden_block_count_y
      - .offset:         496
        .size:           4
        .value_kind:     hidden_block_count_z
      - .offset:         500
        .size:           2
        .value_kind:     hidden_group_size_x
      - .offset:         502
        .size:           2
        .value_kind:     hidden_group_size_y
      - .offset:         504
        .size:           2
        .value_kind:     hidden_group_size_z
      - .offset:         506
        .size:           2
        .value_kind:     hidden_remainder_x
      - .offset:         508
        .size:           2
        .value_kind:     hidden_remainder_y
      - .offset:         510
        .size:           2
        .value_kind:     hidden_remainder_z
      - .offset:         528
        .size:           8
        .value_kind:     hidden_global_offset_x
      - .offset:         536
        .size:           8
        .value_kind:     hidden_global_offset_y
      - .offset:         544
        .size:           8
        .value_kind:     hidden_global_offset_z
      - .offset:         552
        .size:           2
        .value_kind:     hidden_grid_dims
      - .offset:         576
        .size:           8
        .value_kind:     hidden_multigrid_sync_arg
    .group_segment_fixed_size: 73744
    .kernarg_segment_align: 8
    .kernarg_segment_size: 744
    .language:       OpenCL C
    .language_version:
      - 2
      - 0
    .max_flat_workgroup_size: 256
    .name:           _Z2mk1Pii
    .private_segment_fixed_size: 0
    .sgpr_count:     108
    .sgpr_spill_count: 507
    .symbol:         _Z2mk1Pii.kd
    .uniform_work_group_size: 1
    .uses_dynamic_stack: false
    .vgpr_count:     256
    .vgpr_spill_count: 0
    .wavefront_size: 64
